# SwiGLU epilogue rewritten with packed f32 ops: 4.5 VALU per element instead of 11 (same f32 math, products reassociated)
# speedup vs baseline: 1.0177x; 1.0150x over previous
; __device__ __forceinline__ unsigned cvt_pk_bf16(float lo, float hi) { unsigned r; asm("v_cvt_pk_bf16_f32 %0, %1, %2" : "=v"(r) : "v"(lo), "v"(hi)); return r; }
;     __device__ __forceinline__ void operator()(const Acc& acc, const Unit& u, int wr, int wc, int fr, int fq) const {
;         const int row0 = u.pm * BM + wr * 64 + fr, col0 = u.pn * HALF + wc * 32 + 8 * fq;
;         float rrv[8];
; #pragma unroll
;         for (int q = 0; q < 8; ++q) rrv[q] = lr[wr * 64 + fr + (q >> 2) * HALF + (q & 3) * 16];
; #pragma unroll
;         for (int ai = 0; ai < 2; ++ai)
; #pragma unroll
;             for (int m = 0; m < 4; ++m) {
;                 const int row = row0 + ai * HALF + m * 16;
;                 const float rr = rrv[ai * 4 + m];
;                 float r[8];
; #pragma unroll
;                 for (int n = 0; n < 2; ++n)
; #pragma unroll
;                     for (int j = 0; j < 4; ++j) {
;                         const float g = acc[ai][0][m][n][j] * rr, up = acc[ai][1][m][n][j] * rr;
;                         r[n * 4 + j] = g * __builtin_amdgcn_rcpf(1.f + __builtin_amdgcn_exp2f(-g * LOG2E)) * up;
;                     }
;                 u32x4 w; w.x = cvt_pk_bf16(r[0], r[1]); w.y = cvt_pk_bf16(r[2], r[3]); w.z = cvt_pk_bf16(r[4], r[5]); w.w = cvt_pk_bf16(r[6], r[7]);
;                 *(u32x4*)(O + (size_t)row * DFF + col0) = w;
;             }
;     }
.LBB0_684:
	ds_read2_b32 v[144:145], v150 offset1:16
	ds_read2_b32 v[142:143], v150 offset0:32 offset1:48
	ds_read2_b32 v[140:141], v150 offset0:128 offset1:144
	ds_read2_b32 v[138:139], v150 offset0:160 offset1:176
	s_movk_i32 s24, 0x2c00
	s_andn2_b64 vcc, exec, s[14:15]
	s_mov_b32 s49, 0x60000
	s_mov_b32 s52, 0x24000
	s_mov_b32 s53, 0x28000
	s_mov_b32 s58, 0x34000
	s_mov_b32 s59, 0x38000
	s_mov_b32 s60, 0x3c000
	s_mov_b32 s61, 0x44000
	s_mov_b32 s62, 0x48000
	s_mov_b32 s63, 0x4c000
	v_lshl_or_b32 v146, s0, 7, v151
	v_lshl_add_u32 v153, s1, 8, v148
	v_ashrrev_i32_e32 v147, 31, v146
	v_mov_b64_e32 v[154:155], s[10:11]
	v_lshlrev_b64 v[156:157], 1, v[146:147]
	v_mov_b32_e32 v166, 1.0
	s_waitcnt lgkmcnt(0)
	v_mul_f32_e32 v164, 0xbfb8aa3b, v144
	v_mul_f32_e32 v165, v144, v144
	v_pk_mul_f32 v[120:121], v[124:125], v[120:121]
	v_pk_mul_f32 v[122:123], v[126:127], v[122:123]
	v_pk_mul_f32 v[112:113], v[116:117], v[112:113]
	v_pk_mul_f32 v[114:115], v[118:119], v[114:115]
	v_pk_mul_f32 v[124:125], v[124:125], v[164:165] op_sel_hi:[1,0]
	v_pk_mul_f32 v[126:127], v[126:127], v[164:165] op_sel_hi:[1,0]
	v_pk_mul_f32 v[116:117], v[116:117], v[164:165] op_sel_hi:[1,0]
	v_pk_mul_f32 v[118:119], v[118:119], v[164:165] op_sel_hi:[1,0]
	v_exp_f32_e32 v124, v124
	v_exp_f32_e32 v125, v125
	v_exp_f32_e32 v126, v126
	v_exp_f32_e32 v127, v127
	v_exp_f32_e32 v116, v116
	v_exp_f32_e32 v117, v117
	v_exp_f32_e32 v118, v118
	v_exp_f32_e32 v119, v119
	v_pk_mul_f32 v[120:121], v[120:121], v[164:165] op_sel:[0,1] op_sel_hi:[1,1]
	v_pk_mul_f32 v[122:123], v[122:123], v[164:165] op_sel:[0,1] op_sel_hi:[1,1]
	v_pk_mul_f32 v[112:113], v[112:113], v[164:165] op_sel:[0,1] op_sel_hi:[1,1]
	v_pk_mul_f32 v[114:115], v[114:115], v[164:165] op_sel:[0,1] op_sel_hi:[1,1]
	v_pk_add_f32 v[124:125], v[124:125], v[166:167] op_sel_hi:[1,0]
	v_pk_add_f32 v[126:127], v[126:127], v[166:167] op_sel_hi:[1,0]
	v_pk_add_f32 v[116:117], v[116:117], v[166:167] op_sel_hi:[1,0]
	v_pk_add_f32 v[118:119], v[118:119], v[166:167] op_sel_hi:[1,0]
	v_rcp_f32_e32 v124, v124
	v_rcp_f32_e32 v125, v125
	v_rcp_f32_e32 v126, v126
	v_rcp_f32_e32 v127, v127
	v_rcp_f32_e32 v116, v116
	v_rcp_f32_e32 v117, v117
	v_rcp_f32_e32 v118, v118
	v_rcp_f32_e32 v119, v119
	v_mad_i64_i32 v[160:161], s[0:1], v153, s24, v[154:155]
	v_lshl_add_u64 v[160:161], v[160:161], 0, v[156:157]
	v_pk_mul_f32 v[120:121], v[120:121], v[124:125]
	v_pk_mul_f32 v[122:123], v[122:123], v[126:127]
	v_pk_mul_f32 v[112:113], v[112:113], v[116:117]
	v_pk_mul_f32 v[114:115], v[114:115], v[118:119]
	v_cvt_pk_bf16_f32 v124, v120, v121
	v_cvt_pk_bf16_f32 v125, v122, v123
	v_cvt_pk_bf16_f32 v126, v112, v113
	v_cvt_pk_bf16_f32 v127, v114, v115
	global_store_dwordx4 v[160:161], v[124:127], off
	v_mul_f32_e32 v164, 0xbfb8aa3b, v145
	v_mul_f32_e32 v165, v145, v145
	v_pk_mul_f32 v[104:105], v[108:109], v[104:105]
	v_pk_mul_f32 v[106:107], v[110:111], v[106:107]
	v_pk_mul_f32 v[96:97], v[100:101], v[96:97]
	v_pk_mul_f32 v[98:99], v[102:103], v[98:99]
	v_pk_mul_f32 v[108:109], v[108:109], v[164:165] op_sel_hi:[1,0]
	v_pk_mul_f32 v[110:111], v[110:111], v[164:165] op_sel_hi:[1,0]
	v_pk_mul_f32 v[100:101], v[100:101], v[164:165] op_sel_hi:[1,0]
	v_pk_mul_f32 v[102:103], v[102:103], v[164:165] op_sel_hi:[1,0]
	v_exp_f32_e32 v108, v108
	v_exp_f32_e32 v109, v109
	v_exp_f32_e32 v110, v110
	v_exp_f32_e32 v111, v111
	v_exp_f32_e32 v100, v100
	v_exp_f32_e32 v101, v101
	v_exp_f32_e32 v102, v102
	v_exp_f32_e32 v103, v103
	v_pk_mul_f32 v[104:105], v[104:105], v[164:165] op_sel:[0,1] op_sel_hi:[1,1]
	v_pk_mul_f32 v[106:107], v[106:107], v[164:165] op_sel:[0,1] op_sel_hi:[1,1]
	v_pk_mul_f32 v[96:97], v[96:97], v[164:165] op_sel:[0,1] op_sel_hi:[1,1]
	v_pk_mul_f32 v[98:99], v[98:99], v[164:165] op_sel:[0,1] op_sel_hi:[1,1]
	v_pk_add_f32 v[108:109], v[108:109], v[166:167] op_sel_hi:[1,0]
	v_pk_add_f32 v[110:111], v[110:111], v[166:167] op_sel_hi:[1,0]
	v_pk_add_f32 v[100:101], v[100:101], v[166:167] op_sel_hi:[1,0]
	v_pk_add_f32 v[102:103], v[102:103], v[166:167] op_sel_hi:[1,0]
	v_rcp_f32_e32 v108, v108
	v_rcp_f32_e32 v109, v109
	v_rcp_f32_e32 v110, v110
	v_rcp_f32_e32 v111, v111
	v_rcp_f32_e32 v100, v100
	v_rcp_f32_e32 v101, v101
	v_rcp_f32_e32 v102, v102
	v_rcp_f32_e32 v103, v103
	v_add_u32_e32 v158, 0x10, v153
	v_mad_i64_i32 v[162:163], s[0:1], v158, s24, v[154:155]
	v_lshl_add_u64 v[162:163], v[162:163], 0, v[156:157]
	v_pk_mul_f32 v[104:105], v[104:105], v[108:109]
	v_pk_mul_f32 v[106:107], v[106:107], v[110:111]
	v_pk_mul_f32 v[96:97], v[96:97], v[100:101]
	v_pk_mul_f32 v[98:99], v[98:99], v[102:103]
	v_cvt_pk_bf16_f32 v108, v104, v105
	v_cvt_pk_bf16_f32 v109, v106, v107
	v_cvt_pk_bf16_f32 v110, v96, v97
	v_cvt_pk_bf16_f32 v111, v98, v99
	global_store_dwordx4 v[162:163], v[108:111], off
	v_mul_f32_e32 v164, 0xbfb8aa3b, v142
	v_mul_f32_e32 v165, v142, v142
	v_pk_mul_f32 v[88:89], v[92:93], v[88:89]
	v_pk_mul_f32 v[90:91], v[94:95], v[90:91]
	v_pk_mul_f32 v[80:81], v[84:85], v[80:81]
	v_pk_mul_f32 v[82:83], v[86:87], v[82:83]
	v_pk_mul_f32 v[92:93], v[92:93], v[164:165] op_sel_hi:[1,0]
	v_pk_mul_f32 v[94:95], v[94:95], v[164:165] op_sel_hi:[1,0]
	v_pk_mul_f32 v[84:85], v[84:85], v[164:165] op_sel_hi:[1,0]
	v_pk_mul_f32 v[86:87], v[86:87], v[164:165] op_sel_hi:[1,0]
	v_exp_f32_e32 v92, v92
	v_exp_f32_e32 v93, v93
	v_exp_f32_e32 v94, v94
	v_exp_f32_e32 v95, v95
	v_exp_f32_e32 v84, v84
	v_exp_f32_e32 v85, v85
	v_exp_f32_e32 v86, v86
	v_exp_f32_e32 v87, v87
	v_pk_mul_f32 v[88:89], v[88:89], v[164:165] op_sel:[0,1] op_sel_hi:[1,1]
	v_pk_mul_f32 v[90:91], v[90:91], v[164:165] op_sel:[0,1] op_sel_hi:[1,1]
	v_pk_mul_f32 v[80:81], v[80:81], v[164:165] op_sel:[0,1] op_sel_hi:[1,1]
; __device__ __forceinline__ unsigned cvt_pk_bf16(float lo, float hi) { unsigned r; asm("v_cvt_pk_bf16_f32 %0, %1, %2" : "=v"(r) : "v"(lo), "v"(hi)); return r; }
;     __device__ __forceinline__ void operator()(const Acc& acc, const Unit& u, int wr, int wc, int fr, int fq) const {
;         const int row0 = u.pm * BM + wr * 64 + fr, col0 = u.pn * HALF + wc * 32 + 8 * fq;
;         float rrv[8];
; #pragma unroll
;         for (int q = 0; q < 8; ++q) rrv[q] = lr[wr * 64 + fr + (q >> 2) * HALF + (q & 3) * 16];
; #pragma unroll
;         for (int ai = 0; ai < 2; ++ai)
; #pragma unroll
;             for (int m = 0; m < 4; ++m) {
;                 const int row = row0 + ai * HALF + m * 16;
;                 const float rr = rrv[ai * 4 + m];
;                 float r[8];
; #pragma unroll
;                 for (int n = 0; n < 2; ++n)
; #pragma unroll
;                     for (int j = 0; j < 4; ++j) {
;                         const float g = acc[ai][0][m][n][j] * rr, up = acc[ai][1][m][n][j] * rr;
;                         r[n * 4 + j] = g * __builtin_amdgcn_rcpf(1.f + __builtin_amdgcn_exp2f(-g * LOG2E)) * up;
;                     }
;                 u32x4 w; w.x = cvt_pk_bf16(r[0], r[1]); w.y = cvt_pk_bf16(r[2], r[3]); w.z = cvt_pk_bf16(r[4], r[5]); w.w = cvt_pk_bf16(r[6], r[7]);
;                 *(u32x4*)(O + (size_t)row * DFF + col0) = w;
;             }
;     }
	v_pk_mul_f32 v[82:83], v[82:83], v[164:165] op_sel:[0,1] op_sel_hi:[1,1]
	v_pk_add_f32 v[92:93], v[92:93], v[166:167] op_sel_hi:[1,0]
	v_pk_add_f32 v[94:95], v[94:95], v[166:167] op_sel_hi:[1,0]
	v_pk_add_f32 v[84:85], v[84:85], v[166:167] op_sel_hi:[1,0]
	v_pk_add_f32 v[86:87], v[86:87], v[166:167] op_sel_hi:[1,0]
	v_rcp_f32_e32 v92, v92
	v_rcp_f32_e32 v93, v93
	v_rcp_f32_e32 v94, v94
	v_rcp_f32_e32 v95, v95
	v_rcp_f32_e32 v84, v84
	v_rcp_f32_e32 v85, v85
	v_rcp_f32_e32 v86, v86
	v_rcp_f32_e32 v87, v87
	v_add_u32_e32 v158, 0x20, v153
	v_mad_i64_i32 v[160:161], s[0:1], v158, s24, v[154:155]
	v_lshl_add_u64 v[160:161], v[160:161], 0, v[156:157]
	v_pk_mul_f32 v[88:89], v[88:89], v[92:93]
	v_pk_mul_f32 v[90:91], v[90:91], v[94:95]
	v_pk_mul_f32 v[80:81], v[80:81], v[84:85]
	v_pk_mul_f32 v[82:83], v[82:83], v[86:87]
	v_cvt_pk_bf16_f32 v92, v88, v89
	v_cvt_pk_bf16_f32 v93, v90, v91
	v_cvt_pk_bf16_f32 v94, v80, v81
	v_cvt_pk_bf16_f32 v95, v82, v83
	global_store_dwordx4 v[160:161], v[92:95], off
	v_mul_f32_e32 v164, 0xbfb8aa3b, v143
	v_mul_f32_e32 v165, v143, v143
	v_pk_mul_f32 v[72:73], v[76:77], v[72:73]
	v_pk_mul_f32 v[74:75], v[78:79], v[74:75]
	v_pk_mul_f32 v[64:65], v[68:69], v[64:65]
	v_pk_mul_f32 v[66:67], v[70:71], v[66:67]
	v_pk_mul_f32 v[76:77], v[76:77], v[164:165] op_sel_hi:[1,0]
	v_pk_mul_f32 v[78:79], v[78:79], v[164:165] op_sel_hi:[1,0]
	v_pk_mul_f32 v[68:69], v[68:69], v[164:165] op_sel_hi:[1,0]
	v_pk_mul_f32 v[70:71], v[70:71], v[164:165] op_sel_hi:[1,0]
	v_exp_f32_e32 v76, v76
	v_exp_f32_e32 v77, v77
	v_exp_f32_e32 v78, v78
	v_exp_f32_e32 v79, v79
	v_exp_f32_e32 v68, v68
	v_exp_f32_e32 v69, v69
	v_exp_f32_e32 v70, v70
	v_exp_f32_e32 v71, v71
	v_pk_mul_f32 v[72:73], v[72:73], v[164:165] op_sel:[0,1] op_sel_hi:[1,1]
	v_pk_mul_f32 v[74:75], v[74:75], v[164:165] op_sel:[0,1] op_sel_hi:[1,1]
	v_pk_mul_f32 v[64:65], v[64:65], v[164:165] op_sel:[0,1] op_sel_hi:[1,1]
	v_pk_mul_f32 v[66:67], v[66:67], v[164:165] op_sel:[0,1] op_sel_hi:[1,1]
	v_pk_add_f32 v[76:77], v[76:77], v[166:167] op_sel_hi:[1,0]
	v_pk_add_f32 v[78:79], v[78:79], v[166:167] op_sel_hi:[1,0]
	v_pk_add_f32 v[68:69], v[68:69], v[166:167] op_sel_hi:[1,0]
	v_pk_add_f32 v[70:71], v[70:71], v[166:167] op_sel_hi:[1,0]
	v_rcp_f32_e32 v76, v76
	v_rcp_f32_e32 v77, v77
	v_rcp_f32_e32 v78, v78
	v_rcp_f32_e32 v79, v79
	v_rcp_f32_e32 v68, v68
	v_rcp_f32_e32 v69, v69
	v_rcp_f32_e32 v70, v70
	v_rcp_f32_e32 v71, v71
	v_add_u32_e32 v158, 0x30, v153
	v_mad_i64_i32 v[162:163], s[0:1], v158, s24, v[154:155]
	v_lshl_add_u64 v[162:163], v[162:163], 0, v[156:157]
	v_pk_mul_f32 v[72:73], v[72:73], v[76:77]
	v_pk_mul_f32 v[74:75], v[74:75], v[78:79]
	v_pk_mul_f32 v[64:65], v[64:65], v[68:69]
	v_pk_mul_f32 v[66:67], v[66:67], v[70:71]
	v_cvt_pk_bf16_f32 v76, v72, v73
	v_cvt_pk_bf16_f32 v77, v74, v75
	v_cvt_pk_bf16_f32 v78, v64, v65
	v_cvt_pk_bf16_f32 v79, v66, v67
	global_store_dwordx4 v[162:163], v[76:79], off
	v_mul_f32_e32 v164, 0xbfb8aa3b, v140
	v_mul_f32_e32 v165, v140, v140
	v_pk_mul_f32 v[56:57], v[60:61], v[56:57]
	v_pk_mul_f32 v[58:59], v[62:63], v[58:59]
	v_pk_mul_f32 v[48:49], v[52:53], v[48:49]
	v_pk_mul_f32 v[50:51], v[54:55], v[50:51]
	v_pk_mul_f32 v[60:61], v[60:61], v[164:165] op_sel_hi:[1,0]
	v_pk_mul_f32 v[62:63], v[62:63], v[164:165] op_sel_hi:[1,0]
	v_pk_mul_f32 v[52:53], v[52:53], v[164:165] op_sel_hi:[1,0]
	v_pk_mul_f32 v[54:55], v[54:55], v[164:165] op_sel_hi:[1,0]
	v_exp_f32_e32 v60, v60
	v_exp_f32_e32 v61, v61
	v_exp_f32_e32 v62, v62
	v_exp_f32_e32 v63, v63
	v_exp_f32_e32 v52, v52
	v_exp_f32_e32 v53, v53
	v_exp_f32_e32 v54, v54
	v_exp_f32_e32 v55, v55
	v_pk_mul_f32 v[56:57], v[56:57], v[164:165] op_sel:[0,1] op_sel_hi:[1,1]
	v_pk_mul_f32 v[58:59], v[58:59], v[164:165] op_sel:[0,1] op_sel_hi:[1,1]
	v_pk_mul_f32 v[48:49], v[48:49], v[164:165] op_sel:[0,1] op_sel_hi:[1,1]
	v_pk_mul_f32 v[50:51], v[50:51], v[164:165] op_sel:[0,1] op_sel_hi:[1,1]
	v_pk_add_f32 v[60:61], v[60:61], v[166:167] op_sel_hi:[1,0]
	v_pk_add_f32 v[62:63], v[62:63], v[166:167] op_sel_hi:[1,0]
	v_pk_add_f32 v[52:53], v[52:53], v[166:167] op_sel_hi:[1,0]
	v_pk_add_f32 v[54:55], v[54:55], v[166:167] op_sel_hi:[1,0]
	v_rcp_f32_e32 v60, v60
	v_rcp_f32_e32 v61, v61
	v_rcp_f32_e32 v62, v62
	v_rcp_f32_e32 v63, v63
	v_rcp_f32_e32 v52, v52
	v_rcp_f32_e32 v53, v53
	v_rcp_f32_e32 v54, v54
	v_rcp_f32_e32 v55, v55
	v_add_u32_e32 v158, 0x80, v153
	v_mad_i64_i32 v[160:161], s[0:1], v158, s24, v[154:155]
	v_lshl_add_u64 v[160:161], v[160:161], 0, v[156:157]
	v_pk_mul_f32 v[56:57], v[56:57], v[60:61]
	v_pk_mul_f32 v[58:59], v[58:59], v[62:63]
	v_pk_mul_f32 v[48:49], v[48:49], v[52:53]
	v_pk_mul_f32 v[50:51], v[50:51], v[54:55]
	v_cvt_pk_bf16_f32 v60, v56, v57
	v_cvt_pk_bf16_f32 v61, v58, v59
	v_cvt_pk_bf16_f32 v62, v48, v49
	v_cvt_pk_bf16_f32 v63, v50, v51
	global_store_dwordx4 v[160:161], v[60:63], off
	v_mul_f32_e32 v164, 0xbfb8aa3b, v141
	v_mul_f32_e32 v165, v141, v141
	v_pk_mul_f32 v[40:41], v[44:45], v[40:41]
	v_pk_mul_f32 v[42:43], v[46:47], v[42:43]
	v_pk_mul_f32 v[32:33], v[36:37], v[32:33]
	v_pk_mul_f32 v[34:35], v[38:39], v[34:35]
	v_pk_mul_f32 v[44:45], v[44:45], v[164:165] op_sel_hi:[1,0]
	v_pk_mul_f32 v[46:47], v[46:47], v[164:165] op_sel_hi:[1,0]
	v_pk_mul_f32 v[36:37], v[36:37], v[164:165] op_sel_hi:[1,0]
	v_pk_mul_f32 v[38:39], v[38:39], v[164:165] op_sel_hi:[1,0]
; __device__ __forceinline__ unsigned cvt_pk_bf16(float lo, float hi) { unsigned r; asm("v_cvt_pk_bf16_f32 %0, %1, %2" : "=v"(r) : "v"(lo), "v"(hi)); return r; }
;     __device__ __forceinline__ void operator()(const Acc& acc, const Unit& u, int wr, int wc, int fr, int fq) const {
;         const int row0 = u.pm * BM + wr * 64 + fr, col0 = u.pn * HALF + wc * 32 + 8 * fq;
;         float rrv[8];
; #pragma unroll
;         for (int q = 0; q < 8; ++q) rrv[q] = lr[wr * 64 + fr + (q >> 2) * HALF + (q & 3) * 16];
; #pragma unroll
;         for (int ai = 0; ai < 2; ++ai)
; #pragma unroll
;             for (int m = 0; m < 4; ++m) {
;                 const int row = row0 + ai * HALF + m * 16;
;                 const float rr = rrv[ai * 4 + m];
;                 float r[8];
; #pragma unroll
;                 for (int n = 0; n < 2; ++n)
; #pragma unroll
;                     for (int j = 0; j < 4; ++j) {
;                         const float g = acc[ai][0][m][n][j] * rr, up = acc[ai][1][m][n][j] * rr;
;                         r[n * 4 + j] = g * __builtin_amdgcn_rcpf(1.f + __builtin_amdgcn_exp2f(-g * LOG2E)) * up;
;                     }
;                 u32x4 w; w.x = cvt_pk_bf16(r[0], r[1]); w.y = cvt_pk_bf16(r[2], r[3]); w.z = cvt_pk_bf16(r[4], r[5]); w.w = cvt_pk_bf16(r[6], r[7]);
;                 *(u32x4*)(O + (size_t)row * DFF + col0) = w;
;             }
;     }
	v_exp_f32_e32 v44, v44
	v_exp_f32_e32 v45, v45
	v_exp_f32_e32 v46, v46
	v_exp_f32_e32 v47, v47
	v_exp_f32_e32 v36, v36
	v_exp_f32_e32 v37, v37
	v_exp_f32_e32 v38, v38
	v_exp_f32_e32 v39, v39
	v_pk_mul_f32 v[40:41], v[40:41], v[164:165] op_sel:[0,1] op_sel_hi:[1,1]
	v_pk_mul_f32 v[42:43], v[42:43], v[164:165] op_sel:[0,1] op_sel_hi:[1,1]
	v_pk_mul_f32 v[32:33], v[32:33], v[164:165] op_sel:[0,1] op_sel_hi:[1,1]
	v_pk_mul_f32 v[34:35], v[34:35], v[164:165] op_sel:[0,1] op_sel_hi:[1,1]
	v_pk_add_f32 v[44:45], v[44:45], v[166:167] op_sel_hi:[1,0]
	v_pk_add_f32 v[46:47], v[46:47], v[166:167] op_sel_hi:[1,0]
	v_pk_add_f32 v[36:37], v[36:37], v[166:167] op_sel_hi:[1,0]
	v_pk_add_f32 v[38:39], v[38:39], v[166:167] op_sel_hi:[1,0]
	v_rcp_f32_e32 v44, v44
	v_rcp_f32_e32 v45, v45
	v_rcp_f32_e32 v46, v46
	v_rcp_f32_e32 v47, v47
	v_rcp_f32_e32 v36, v36
	v_rcp_f32_e32 v37, v37
	v_rcp_f32_e32 v38, v38
	v_rcp_f32_e32 v39, v39
	v_add_u32_e32 v158, 0x90, v153
	v_mad_i64_i32 v[162:163], s[0:1], v158, s24, v[154:155]
	v_lshl_add_u64 v[162:163], v[162:163], 0, v[156:157]
	v_pk_mul_f32 v[40:41], v[40:41], v[44:45]
	v_pk_mul_f32 v[42:43], v[42:43], v[46:47]
	v_pk_mul_f32 v[32:33], v[32:33], v[36:37]
	v_pk_mul_f32 v[34:35], v[34:35], v[38:39]
	v_cvt_pk_bf16_f32 v44, v40, v41
	v_cvt_pk_bf16_f32 v45, v42, v43
	v_cvt_pk_bf16_f32 v46, v32, v33
	v_cvt_pk_bf16_f32 v47, v34, v35
	global_store_dwordx4 v[162:163], v[44:47], off
	v_mul_f32_e32 v164, 0xbfb8aa3b, v138
	v_mul_f32_e32 v165, v138, v138
	v_pk_mul_f32 v[24:25], v[28:29], v[24:25]
	v_pk_mul_f32 v[26:27], v[30:31], v[26:27]
	v_pk_mul_f32 v[16:17], v[20:21], v[16:17]
	v_pk_mul_f32 v[18:19], v[22:23], v[18:19]
	v_pk_mul_f32 v[28:29], v[28:29], v[164:165] op_sel_hi:[1,0]
	v_pk_mul_f32 v[30:31], v[30:31], v[164:165] op_sel_hi:[1,0]
	v_pk_mul_f32 v[20:21], v[20:21], v[164:165] op_sel_hi:[1,0]
	v_pk_mul_f32 v[22:23], v[22:23], v[164:165] op_sel_hi:[1,0]
	v_exp_f32_e32 v28, v28
	v_exp_f32_e32 v29, v29
	v_exp_f32_e32 v30, v30
	v_exp_f32_e32 v31, v31
	v_exp_f32_e32 v20, v20
	v_exp_f32_e32 v21, v21
	v_exp_f32_e32 v22, v22
	v_exp_f32_e32 v23, v23
	v_pk_mul_f32 v[24:25], v[24:25], v[164:165] op_sel:[0,1] op_sel_hi:[1,1]
	v_pk_mul_f32 v[26:27], v[26:27], v[164:165] op_sel:[0,1] op_sel_hi:[1,1]
	v_pk_mul_f32 v[16:17], v[16:17], v[164:165] op_sel:[0,1] op_sel_hi:[1,1]
	v_pk_mul_f32 v[18:19], v[18:19], v[164:165] op_sel:[0,1] op_sel_hi:[1,1]
	v_pk_add_f32 v[28:29], v[28:29], v[166:167] op_sel_hi:[1,0]
	v_pk_add_f32 v[30:31], v[30:31], v[166:167] op_sel_hi:[1,0]
	v_pk_add_f32 v[20:21], v[20:21], v[166:167] op_sel_hi:[1,0]
	v_pk_add_f32 v[22:23], v[22:23], v[166:167] op_sel_hi:[1,0]
	v_rcp_f32_e32 v28, v28
	v_rcp_f32_e32 v29, v29
	v_rcp_f32_e32 v30, v30
	v_rcp_f32_e32 v31, v31
	v_rcp_f32_e32 v20, v20
	v_rcp_f32_e32 v21, v21
	v_rcp_f32_e32 v22, v22
	v_rcp_f32_e32 v23, v23
	v_add_u32_e32 v158, 0xa0, v153
	v_mad_i64_i32 v[160:161], s[0:1], v158, s24, v[154:155]
	v_lshl_add_u64 v[160:161], v[160:161], 0, v[156:157]
	v_pk_mul_f32 v[24:25], v[24:25], v[28:29]
	v_pk_mul_f32 v[26:27], v[26:27], v[30:31]
	v_pk_mul_f32 v[16:17], v[16:17], v[20:21]
	v_pk_mul_f32 v[18:19], v[18:19], v[22:23]
	v_cvt_pk_bf16_f32 v28, v24, v25
	v_cvt_pk_bf16_f32 v29, v26, v27
	v_cvt_pk_bf16_f32 v30, v16, v17
	v_cvt_pk_bf16_f32 v31, v18, v19
	global_store_dwordx4 v[160:161], v[28:31], off
	v_mul_f32_e32 v164, 0xbfb8aa3b, v139
	v_mul_f32_e32 v165, v139, v139
	v_pk_mul_f32 v[8:9], v[12:13], v[8:9]
	v_pk_mul_f32 v[10:11], v[14:15], v[10:11]
	v_pk_mul_f32 v[0:1], v[4:5], v[0:1]
	v_pk_mul_f32 v[2:3], v[6:7], v[2:3]
	v_pk_mul_f32 v[12:13], v[12:13], v[164:165] op_sel_hi:[1,0]
	v_pk_mul_f32 v[14:15], v[14:15], v[164:165] op_sel_hi:[1,0]
	v_pk_mul_f32 v[4:5], v[4:5], v[164:165] op_sel_hi:[1,0]
	v_pk_mul_f32 v[6:7], v[6:7], v[164:165] op_sel_hi:[1,0]
	v_exp_f32_e32 v12, v12
	v_exp_f32_e32 v13, v13
	v_exp_f32_e32 v14, v14
	v_exp_f32_e32 v15, v15
	v_exp_f32_e32 v4, v4
	v_exp_f32_e32 v5, v5
	v_exp_f32_e32 v6, v6
	v_exp_f32_e32 v7, v7
	v_pk_mul_f32 v[8:9], v[8:9], v[164:165] op_sel:[0,1] op_sel_hi:[1,1]
	v_pk_mul_f32 v[10:11], v[10:11], v[164:165] op_sel:[0,1] op_sel_hi:[1,1]
	v_pk_mul_f32 v[0:1], v[0:1], v[164:165] op_sel:[0,1] op_sel_hi:[1,1]
	v_pk_mul_f32 v[2:3], v[2:3], v[164:165] op_sel:[0,1] op_sel_hi:[1,1]
	v_pk_add_f32 v[12:13], v[12:13], v[166:167] op_sel_hi:[1,0]
	v_pk_add_f32 v[14:15], v[14:15], v[166:167] op_sel_hi:[1,0]
	v_pk_add_f32 v[4:5], v[4:5], v[166:167] op_sel_hi:[1,0]
	v_pk_add_f32 v[6:7], v[6:7], v[166:167] op_sel_hi:[1,0]
	v_rcp_f32_e32 v12, v12
	v_rcp_f32_e32 v13, v13
	v_rcp_f32_e32 v14, v14
	v_rcp_f32_e32 v15, v15
	v_rcp_f32_e32 v4, v4
	v_rcp_f32_e32 v5, v5
	v_rcp_f32_e32 v6, v6
	v_rcp_f32_e32 v7, v7
	v_add_u32_e32 v158, 0xb0, v153
	v_mad_i64_i32 v[162:163], s[0:1], v158, s24, v[154:155]
	v_lshl_add_u64 v[162:163], v[162:163], 0, v[156:157]
	v_pk_mul_f32 v[8:9], v[8:9], v[12:13]
	v_pk_mul_f32 v[10:11], v[10:11], v[14:15]
	v_pk_mul_f32 v[0:1], v[0:1], v[4:5]
	v_pk_mul_f32 v[2:3], v[2:3], v[6:7]
	v_cvt_pk_bf16_f32 v12, v8, v9
	v_cvt_pk_bf16_f32 v13, v10, v11
	v_cvt_pk_bf16_f32 v14, v0, v1
	v_cvt_pk_bf16_f32 v15, v2, v3
	s_mov_b64 s[0:1], -1
	global_store_dwordx4 v[162:163], v[12:15], off
	s_cbranch_vccnz .LBB0_679
	s_andn2_b64 vcc, exec, s[8:9]
	s_cbranch_vccnz .LBB0_678
	s_barrier
	s_branch .LBB0_678
